# layer-1 memory attention body: second wave of each SIMD starts 1536 cycles late so MFMA/LDS stages meet the partner's VALU stages
# speedup vs baseline: 1.0034x; 1.0014x over previous
.LBB0_577:
	s_mov_b32 s13, 0xff61b1e6
	v_readfirstlane_b32 s8, v194
	s_nop 3
	s_cmp_lt_u32 s8, 256
	s_cbranch_scc1 .Lma_nostag
	s_sleep 24
.Lma_nostag:
	v_add_u32_e32 v150, 0x9000, v122
	v_add_u32_e32 v151, 0x9000, v123
	v_add_u32_e32 v152, 0x9000, v124
	v_add_u32_e32 v153, 0x9000, v125
	ds_read_b128 v[200:203], v128
	ds_read_b128 v[204:207], v128 offset:64
	ds_read_b128 v[208:211], v128 offset:2304
	ds_read_b128 v[212:215], v128 offset:2368
	ds_read_b128 v[216:219], v128 offset:4608
	ds_read_b128 v[220:223], v128 offset:4672
	ds_read_b128 v[224:227], v128 offset:6912
	ds_read_b128 v[228:231], v128 offset:6976
	s_waitcnt vmcnt(10)
	s_waitcnt lgkmcnt(4)
	v_mfma_f32_16x16x32_bf16 v[44:47], v[200:203], v[108:111], 0
	v_mfma_f32_16x16x32_bf16 v[48:51], v[208:211], v[108:111], 0
	v_mfma_f32_16x16x32_bf16 v[44:47], v[204:207], v[60:63], v[44:47]
	v_mfma_f32_16x16x32_bf16 v[48:51], v[212:215], v[60:63], v[48:51]
	ds_read_b128 v[200:203], v128 offset:9216
	ds_read_b128 v[204:207], v128 offset:9280
	ds_read_b128 v[208:211], v128 offset:11520
	ds_read_b128 v[212:215], v128 offset:11584
	s_waitcnt lgkmcnt(4)
	v_mfma_f32_16x16x32_bf16 v[52:55], v[216:219], v[108:111], 0
	v_mfma_f32_16x16x32_bf16 v[56:59], v[224:227], v[108:111], 0
	v_mfma_f32_16x16x32_bf16 v[52:55], v[220:223], v[60:63], v[52:55]
	v_mfma_f32_16x16x32_bf16 v[56:59], v[228:231], v[60:63], v[56:59]
	ds_read_b128 v[216:219], v128 offset:13824
	ds_read_b128 v[220:223], v128 offset:13888
	ds_read_b128 v[224:227], v128 offset:16128
	ds_read_b128 v[228:231], v128 offset:16192
	s_waitcnt lgkmcnt(4)
	v_mfma_f32_16x16x32_bf16 v[64:67], v[200:203], v[108:111], 0
	v_mfma_f32_16x16x32_bf16 v[68:71], v[208:211], v[108:111], 0
	v_mfma_f32_16x16x32_bf16 v[64:67], v[204:207], v[60:63], v[64:67]
	v_mfma_f32_16x16x32_bf16 v[68:71], v[212:215], v[60:63], v[68:71]
	ds_read_b128 v[200:203], v128 offset:18432
	ds_read_b128 v[204:207], v128 offset:18496
	ds_read_b128 v[208:211], v128 offset:20736
	ds_read_b128 v[212:215], v128 offset:20800
	s_waitcnt lgkmcnt(4)
	v_mfma_f32_16x16x32_bf16 v[72:75], v[216:219], v[108:111], 0
	v_mfma_f32_16x16x32_bf16 v[76:79], v[224:227], v[108:111], 0
	v_mfma_f32_16x16x32_bf16 v[72:75], v[220:223], v[60:63], v[72:75]
	v_mfma_f32_16x16x32_bf16 v[76:79], v[228:231], v[60:63], v[76:79]
	ds_read_b128 v[216:219], v128 offset:23040
	ds_read_b128 v[220:223], v128 offset:23104
	ds_read_b128 v[224:227], v128 offset:25344
	ds_read_b128 v[228:231], v128 offset:25408
	s_waitcnt lgkmcnt(4)
	v_mfma_f32_16x16x32_bf16 v[80:83], v[200:203], v[108:111], 0
	v_mfma_f32_16x16x32_bf16 v[84:87], v[208:211], v[108:111], 0
	v_mfma_f32_16x16x32_bf16 v[80:83], v[204:207], v[60:63], v[80:83]
	v_mfma_f32_16x16x32_bf16 v[84:87], v[212:215], v[60:63], v[84:87]
	ds_read_b128 v[200:203], v128 offset:27648
	ds_read_b128 v[204:207], v128 offset:27712
	ds_read_b128 v[208:211], v128 offset:29952
	ds_read_b128 v[212:215], v128 offset:30016
	s_waitcnt lgkmcnt(4)
	v_mfma_f32_16x16x32_bf16 v[88:91], v[216:219], v[108:111], 0
	v_mfma_f32_16x16x32_bf16 v[92:95], v[224:227], v[108:111], 0
	v_mfma_f32_16x16x32_bf16 v[88:91], v[220:223], v[60:63], v[88:91]
	v_mfma_f32_16x16x32_bf16 v[92:95], v[228:231], v[60:63], v[92:95]
	ds_read_b128 v[216:219], v128 offset:32256
	ds_read_b128 v[220:223], v128 offset:32320
	ds_read_b128 v[224:227], v128 offset:34560
	ds_read_b128 v[228:231], v128 offset:34624
	s_waitcnt lgkmcnt(4)
	v_mfma_f32_16x16x32_bf16 v[96:99], v[200:203], v[108:111], 0
	v_mfma_f32_16x16x32_bf16 v[100:103], v[208:211], v[108:111], 0
	v_mfma_f32_16x16x32_bf16 v[96:99], v[204:207], v[60:63], v[96:99]
	v_mfma_f32_16x16x32_bf16 v[100:103], v[212:215], v[60:63], v[100:103]
	s_waitcnt lgkmcnt(0)
	v_mfma_f32_16x16x32_bf16 v[104:107], v[216:219], v[108:111], 0
	v_mfma_f32_16x16x32_bf16 v[130:133], v[224:227], v[108:111], 0
	v_mfma_f32_16x16x32_bf16 v[104:107], v[220:223], v[60:63], v[104:107]
	v_mfma_f32_16x16x32_bf16 v[130:133], v[228:231], v[60:63], v[130:133]
	s_nop 7
	v_max3_f32 v154, v44, v45, s13
	v_max3_f32 v154, v46, v47, v154
	v_max3_f32 v154, v48, v49, v154
	v_max3_f32 v154, v50, v51, v154
	v_max3_f32 v154, v52, v53, v154
	v_max3_f32 v154, v54, v55, v154
	v_max3_f32 v154, v56, v57, v154
	v_max3_f32 v154, v58, v59, v154
	v_max3_f32 v154, v64, v65, v154
	v_max3_f32 v154, v66, v67, v154
	v_max3_f32 v154, v68, v69, v154
	v_max3_f32 v154, v70, v71, v154
	v_max3_f32 v154, v72, v73, v154
	v_max3_f32 v154, v74, v75, v154
	v_max3_f32 v154, v76, v77, v154
	v_max3_f32 v154, v78, v79, v154
	v_max3_f32 v154, v80, v81, v154
	v_max3_f32 v154, v82, v83, v154
	v_max3_f32 v154, v84, v85, v154
	v_max3_f32 v154, v86, v87, v154
	v_max3_f32 v154, v88, v89, v154
	v_max3_f32 v154, v90, v91, v154
	v_max3_f32 v154, v92, v93, v154
	v_max3_f32 v154, v94, v95, v154
	v_max3_f32 v154, v96, v97, v154
	v_max3_f32 v154, v98, v99, v154
	v_max3_f32 v154, v100, v101, v154
	v_max3_f32 v154, v102, v103, v154
	v_max3_f32 v154, v104, v105, v154
	v_max3_f32 v154, v106, v107, v154
	v_max3_f32 v154, v130, v131, v154
	v_max3_f32 v154, v132, v133, v154
	ds_bpermute_b32 v155, v126, v154
	s_waitcnt lgkmcnt(0)
	v_max_f32_e32 v154, v154, v155
	ds_bpermute_b32 v155, v127, v154
	s_waitcnt lgkmcnt(0)
	v_max_f32_e32 v154, v154, v155
	v_sub_f32_e32 v44, v44, v154
	v_exp_f32_e32 v44, v44
	v_sub_f32_e32 v45, v45, v154
	v_exp_f32_e32 v45, v45
	v_add_f32_e32 v172, 0, v44
	v_sub_f32_e32 v46, v46, v154
	v_exp_f32_e32 v46, v46
	v_add_f32_e32 v172, v45, v172
	v_sub_f32_e32 v47, v47, v154
	v_exp_f32_e32 v47, v47
	v_add_f32_e32 v172, v46, v172
	v_sub_f32_e32 v48, v48, v154
	v_exp_f32_e32 v48, v48
	v_add_f32_e32 v172, v47, v172
	v_sub_f32_e32 v49, v49, v154
	v_exp_f32_e32 v49, v49
	v_add_f32_e32 v172, v48, v172
	v_sub_f32_e32 v50, v50, v154
	v_exp_f32_e32 v50, v50
	v_add_f32_e32 v172, v49, v172
	v_sub_f32_e32 v51, v51, v154
	v_exp_f32_e32 v51, v51
	v_add_f32_e32 v172, v50, v172
	v_sub_f32_e32 v52, v52, v154
	v_exp_f32_e32 v52, v52
	v_add_f32_e32 v172, v51, v172
	v_sub_f32_e32 v53, v53, v154
	v_exp_f32_e32 v53, v53
	v_add_f32_e32 v172, v52, v172
	v_sub_f32_e32 v54, v54, v154
	v_exp_f32_e32 v54, v54
	v_add_f32_e32 v172, v53, v172
	v_sub_f32_e32 v55, v55, v154
	v_exp_f32_e32 v55, v55
	v_add_f32_e32 v172, v54, v172
	v_sub_f32_e32 v56, v56, v154
	v_exp_f32_e32 v56, v56
	v_add_f32_e32 v172, v55, v172
	v_sub_f32_e32 v57, v57, v154
	v_exp_f32_e32 v57, v57
	v_add_f32_e32 v172, v56, v172
	v_sub_f32_e32 v58, v58, v154
	v_exp_f32_e32 v58, v58
	v_add_f32_e32 v172, v57, v172
	v_sub_f32_e32 v59, v59, v154
	v_exp_f32_e32 v59, v59
	v_add_f32_e32 v172, v58, v172
	v_sub_f32_e32 v64, v64, v154
	v_exp_f32_e32 v64, v64
	v_add_f32_e32 v172, v59, v172
	v_sub_f32_e32 v65, v65, v154
	v_exp_f32_e32 v65, v65
	v_add_f32_e32 v172, v64, v172
	v_sub_f32_e32 v66, v66, v154
	v_exp_f32_e32 v66, v66
	v_add_f32_e32 v172, v65, v172
	v_sub_f32_e32 v67, v67, v154
	v_exp_f32_e32 v67, v67
	v_add_f32_e32 v172, v66, v172
	v_sub_f32_e32 v68, v68, v154
	v_exp_f32_e32 v68, v68
	v_add_f32_e32 v172, v67, v172
	v_sub_f32_e32 v69, v69, v154
	v_exp_f32_e32 v69, v69
	v_add_f32_e32 v172, v68, v172
	v_sub_f32_e32 v70, v70, v154
	v_exp_f32_e32 v70, v70
	v_add_f32_e32 v172, v69, v172
	v_sub_f32_e32 v71, v71, v154
	v_exp_f32_e32 v71, v71
	v_add_f32_e32 v172, v70, v172
	v_sub_f32_e32 v72, v72, v154
	v_exp_f32_e32 v72, v72
	v_add_f32_e32 v172, v71, v172
	v_sub_f32_e32 v73, v73, v154
	v_exp_f32_e32 v73, v73
	v_add_f32_e32 v172, v72, v172
	v_sub_f32_e32 v74, v74, v154
	v_exp_f32_e32 v74, v74
	v_add_f32_e32 v172, v73, v172
	v_sub_f32_e32 v75, v75, v154
	v_exp_f32_e32 v75, v75
	v_add_f32_e32 v172, v74, v172
	v_sub_f32_e32 v76, v76, v154
	v_exp_f32_e32 v76, v76
	v_add_f32_e32 v172, v75, v172
	v_sub_f32_e32 v77, v77, v154
	v_exp_f32_e32 v77, v77
	v_add_f32_e32 v172, v76, v172
	v_sub_f32_e32 v78, v78, v154
	v_exp_f32_e32 v78, v78
	v_add_f32_e32 v172, v77, v172
	v_sub_f32_e32 v79, v79, v154
	v_exp_f32_e32 v79, v79
	v_add_f32_e32 v172, v78, v172
	v_sub_f32_e32 v80, v80, v154
	v_exp_f32_e32 v80, v80
	v_add_f32_e32 v172, v79, v172
	v_sub_f32_e32 v81, v81, v154
	v_exp_f32_e32 v81, v81
	v_add_f32_e32 v172, v80, v172
	v_sub_f32_e32 v82, v82, v154
	v_exp_f32_e32 v82, v82
	v_add_f32_e32 v172, v81, v172
	v_sub_f32_e32 v83, v83, v154
	v_exp_f32_e32 v83, v83
	v_add_f32_e32 v172, v82, v172
	v_sub_f32_e32 v84, v84, v154
	v_exp_f32_e32 v84, v84
	v_add_f32_e32 v172, v83, v172
	v_sub_f32_e32 v85, v85, v154
	v_exp_f32_e32 v85, v85
	v_add_f32_e32 v172, v84, v172
	v_sub_f32_e32 v86, v86, v154
	v_exp_f32_e32 v86, v86
	v_add_f32_e32 v172, v85, v172
	v_sub_f32_e32 v87, v87, v154
	v_exp_f32_e32 v87, v87
	v_add_f32_e32 v172, v86, v172
	v_sub_f32_e32 v88, v88, v154
	v_exp_f32_e32 v88, v88
	v_add_f32_e32 v172, v87, v172
	v_sub_f32_e32 v89, v89, v154
	v_exp_f32_e32 v89, v89
	v_add_f32_e32 v172, v88, v172
	v_sub_f32_e32 v90, v90, v154
	v_exp_f32_e32 v90, v90
	v_add_f32_e32 v172, v89, v172
	v_sub_f32_e32 v91, v91, v154
	v_exp_f32_e32 v91, v91
	v_add_f32_e32 v172, v90, v172
	v_sub_f32_e32 v92, v92, v154
	v_exp_f32_e32 v92, v92
	v_add_f32_e32 v172, v91, v172
	v_sub_f32_e32 v93, v93, v154
	v_exp_f32_e32 v93, v93
	v_add_f32_e32 v172, v92, v172
	v_sub_f32_e32 v94, v94, v154
	v_exp_f32_e32 v94, v94
	v_add_f32_e32 v172, v93, v172
	v_sub_f32_e32 v95, v95, v154
	v_exp_f32_e32 v95, v95
	v_add_f32_e32 v172, v94, v172
	v_sub_f32_e32 v96, v96, v154
	v_exp_f32_e32 v96, v96
	v_add_f32_e32 v172, v95, v172
	v_sub_f32_e32 v97, v97, v154
	v_exp_f32_e32 v97, v97
	v_add_f32_e32 v172, v96, v172
	v_sub_f32_e32 v98, v98, v154
	v_exp_f32_e32 v98, v98
	v_add_f32_e32 v172, v97, v172
	v_sub_f32_e32 v99, v99, v154
	v_exp_f32_e32 v99, v99
	v_add_f32_e32 v172, v98, v172
	v_sub_f32_e32 v100, v100, v154
	v_exp_f32_e32 v100, v100
	v_add_f32_e32 v172, v99, v172
	v_sub_f32_e32 v101, v101, v154
	v_exp_f32_e32 v101, v101
	v_add_f32_e32 v172, v100, v172
	v_sub_f32_e32 v102, v102, v154
	v_exp_f32_e32 v102, v102
	v_add_f32_e32 v172, v101, v172
	v_sub_f32_e32 v103, v103, v154
	v_exp_f32_e32 v103, v103
	v_add_f32_e32 v172, v102, v172
	v_sub_f32_e32 v104, v104, v154
	v_exp_f32_e32 v104, v104
	v_add_f32_e32 v172, v103, v172
	v_sub_f32_e32 v105, v105, v154
	v_exp_f32_e32 v105, v105
	v_add_f32_e32 v172, v104, v172
	v_sub_f32_e32 v106, v106, v154
	v_exp_f32_e32 v106, v106
	v_add_f32_e32 v172, v105, v172
	v_sub_f32_e32 v107, v107, v154
	v_exp_f32_e32 v107, v107
	v_add_f32_e32 v172, v106, v172
	v_sub_f32_e32 v130, v130, v154
	v_exp_f32_e32 v130, v130
	v_add_f32_e32 v172, v107, v172
	v_sub_f32_e32 v131, v131, v154
	v_exp_f32_e32 v131, v131
	v_add_f32_e32 v172, v130, v172
	v_sub_f32_e32 v132, v132, v154
	v_exp_f32_e32 v132, v132
	v_add_f32_e32 v172, v131, v172
	v_sub_f32_e32 v133, v133, v154
	v_exp_f32_e32 v133, v133
	v_add_f32_e32 v172, v132, v172
	s_nop 0
	v_add_f32_e32 v172, v133, v172
	ds_bpermute_b32 v155, v126, v172
	s_waitcnt lgkmcnt(0)
	v_add_f32_e32 v172, v172, v155
	ds_bpermute_b32 v155, v127, v172
	s_waitcnt lgkmcnt(0)
	v_add_f32_e32 v172, v172, v155
	ds_read2_b64 v[200:203], v150 offset0:0 offset1:4
	ds_read2_b64 v[204:207], v151 offset0:0 offset1:4
	ds_read2_b64 v[208:211], v152 offset0:0 offset1:4
	ds_read2_b64 v[212:215], v153 offset0:0 offset1:4
	ds_read2_b64 v[216:219], v150 offset0:8 offset1:12
	ds_read2_b64 v[220:223], v151 offset0:8 offset1:12
	ds_read2_b64 v[224:227], v152 offset0:8 offset1:12
	ds_read2_b64 v[228:231], v153 offset0:8 offset1:12
	v_cvt_pk_bf16_f32 v44, v44, v45
	v_cvt_pk_bf16_f32 v45, v46, v47
	v_cvt_pk_bf16_f32 v46, v48, v49
	v_cvt_pk_bf16_f32 v47, v50, v51
	v_cvt_pk_bf16_f32 v52, v52, v53
	v_cvt_pk_bf16_f32 v53, v54, v55
	v_cvt_pk_bf16_f32 v54, v56, v57
	v_cvt_pk_bf16_f32 v55, v58, v59
	s_waitcnt lgkmcnt(4)
	s_nop 1
	v_mfma_f32_16x16x32_bf16 v[134:137], v[200:203], v[44:47], 0
	v_mfma_f32_16x16x32_bf16 v[138:141], v[204:207], v[44:47], 0
	v_mfma_f32_16x16x32_bf16 v[142:145], v[208:211], v[44:47], 0
	v_mfma_f32_16x16x32_bf16 v[146:149], v[212:215], v[44:47], 0
	ds_read2_b64 v[200:203], v150 offset0:16 offset1:20
	ds_read2_b64 v[204:207], v151 offset0:16 offset1:20
	ds_read2_b64 v[208:211], v152 offset0:16 offset1:20
	ds_read2_b64 v[212:215], v153 offset0:16 offset1:20
	v_cvt_pk_bf16_f32 v64, v64, v65
	v_cvt_pk_bf16_f32 v65, v66, v67
	v_cvt_pk_bf16_f32 v66, v68, v69
	v_cvt_pk_bf16_f32 v67, v70, v71
	s_waitcnt lgkmcnt(4)
	s_nop 1
	v_mfma_f32_16x16x32_bf16 v[134:137], v[216:219], v[52:55], v[134:137]
	v_mfma_f32_16x16x32_bf16 v[138:141], v[220:223], v[52:55], v[138:141]
	v_mfma_f32_16x16x32_bf16 v[142:145], v[224:227], v[52:55], v[142:145]
	v_mfma_f32_16x16x32_bf16 v[146:149], v[228:231], v[52:55], v[146:149]
	ds_read2_b64 v[216:219], v150 offset0:24 offset1:28
	ds_read2_b64 v[220:223], v151 offset0:24 offset1:28
	ds_read2_b64 v[224:227], v152 offset0:24 offset1:28
	ds_read2_b64 v[228:231], v153 offset0:24 offset1:28
	v_cvt_pk_bf16_f32 v72, v72, v73
	v_cvt_pk_bf16_f32 v73, v74, v75
	v_cvt_pk_bf16_f32 v74, v76, v77
	v_cvt_pk_bf16_f32 v75, v78, v79
	s_waitcnt lgkmcnt(4)
	s_nop 1
	v_mfma_f32_16x16x32_bf16 v[134:137], v[200:203], v[64:67], v[134:137]
	v_mfma_f32_16x16x32_bf16 v[138:141], v[204:207], v[64:67], v[138:141]
	v_mfma_f32_16x16x32_bf16 v[142:145], v[208:211], v[64:67], v[142:145]
	v_mfma_f32_16x16x32_bf16 v[146:149], v[212:215], v[64:67], v[146:149]
	ds_read2_b64 v[200:203], v150 offset0:32 offset1:36
	ds_read2_b64 v[204:207], v151 offset0:32 offset1:36
	ds_read2_b64 v[208:211], v152 offset0:32 offset1:36
	ds_read2_b64 v[212:215], v153 offset0:32 offset1:36
	v_cvt_pk_bf16_f32 v80, v80, v81
	v_cvt_pk_bf16_f32 v81, v82, v83
	v_cvt_pk_bf16_f32 v82, v84, v85
	v_cvt_pk_bf16_f32 v83, v86, v87
	s_waitcnt lgkmcnt(4)
	s_nop 1
	v_mfma_f32_16x16x32_bf16 v[134:137], v[216:219], v[72:75], v[134:137]
	v_mfma_f32_16x16x32_bf16 v[138:141], v[220:223], v[72:75], v[138:141]
	v_mfma_f32_16x16x32_bf16 v[142:145], v[224:227], v[72:75], v[142:145]
	v_mfma_f32_16x16x32_bf16 v[146:149], v[228:231], v[72:75], v[146:149]
	ds_read2_b64 v[216:219], v150 offset0:40 offset1:44
	ds_read2_b64 v[220:223], v151 offset0:40 offset1:44
	ds_read2_b64 v[224:227], v152 offset0:40 offset1:44
	ds_read2_b64 v[228:231], v153 offset0:40 offset1:44
	v_cvt_pk_bf16_f32 v88, v88, v89
	v_cvt_pk_bf16_f32 v89, v90, v91
	v_cvt_pk_bf16_f32 v90, v92, v93
	v_cvt_pk_bf16_f32 v91, v94, v95
	s_waitcnt lgkmcnt(4)
	s_nop 1
	v_mfma_f32_16x16x32_bf16 v[134:137], v[200:203], v[80:83], v[134:137]
	v_mfma_f32_16x16x32_bf16 v[138:141], v[204:207], v[80:83], v[138:141]
	v_mfma_f32_16x16x32_bf16 v[142:145], v[208:211], v[80:83], v[142:145]
	v_mfma_f32_16x16x32_bf16 v[146:149], v[212:215], v[80:83], v[146:149]
	ds_read2_b64 v[200:203], v150 offset0:48 offset1:52
	ds_read2_b64 v[204:207], v151 offset0:48 offset1:52
	ds_read2_b64 v[208:211], v152 offset0:48 offset1:52
	ds_read2_b64 v[212:215], v153 offset0:48 offset1:52
	v_cvt_pk_bf16_f32 v96, v96, v97
	v_cvt_pk_bf16_f32 v97, v98, v99
	v_cvt_pk_bf16_f32 v98, v100, v101
	v_cvt_pk_bf16_f32 v99, v102, v103
	s_waitcnt lgkmcnt(4)
	s_nop 1
	v_mfma_f32_16x16x32_bf16 v[134:137], v[216:219], v[88:91], v[134:137]
	v_mfma_f32_16x16x32_bf16 v[138:141], v[220:223], v[88:91], v[138:141]
	v_mfma_f32_16x16x32_bf16 v[142:145], v[224:227], v[88:91], v[142:145]
	v_mfma_f32_16x16x32_bf16 v[146:149], v[228:231], v[88:91], v[146:149]
	ds_read2_b64 v[216:219], v150 offset0:56 offset1:60
	ds_read2_b64 v[220:223], v151 offset0:56 offset1:60
	ds_read2_b64 v[224:227], v152 offset0:56 offset1:60
	ds_read2_b64 v[228:231], v153 offset0:56 offset1:60
	v_cvt_pk_bf16_f32 v104, v104, v105
	v_cvt_pk_bf16_f32 v105, v106, v107
	v_cvt_pk_bf16_f32 v106, v130, v131
	v_cvt_pk_bf16_f32 v107, v132, v133
	s_waitcnt lgkmcnt(4)
	s_nop 1
	v_mfma_f32_16x16x32_bf16 v[134:137], v[200:203], v[96:99], v[134:137]
	v_mfma_f32_16x16x32_bf16 v[138:141], v[204:207], v[96:99], v[138:141]
	v_mfma_f32_16x16x32_bf16 v[142:145], v[208:211], v[96:99], v[142:145]
	v_mfma_f32_16x16x32_bf16 v[146:149], v[212:215], v[96:99], v[146:149]
	s_waitcnt lgkmcnt(0)
	s_nop 1
	v_mfma_f32_16x16x32_bf16 v[134:137], v[216:219], v[104:107], v[134:137]
	v_mfma_f32_16x16x32_bf16 v[138:141], v[220:223], v[104:107], v[138:141]
	v_mfma_f32_16x16x32_bf16 v[142:145], v[224:227], v[104:107], v[142:145]
	v_mfma_f32_16x16x32_bf16 v[146:149], v[228:231], v[104:107], v[146:149]
	v_div_scale_f32 v173, s[8:9], v172, v172, 1.0
	v_rcp_f32_e32 v175, v173
	s_nop 0
	v_fma_f32 v176, -v173, v175, 1.0
	v_fmac_f32_e32 v175, v176, v175
	v_div_scale_f32 v174, vcc, 1.0, v172, 1.0
	v_mul_f32_e32 v177, v174, v175
	v_fma_f32 v176, -v173, v177, v174
	v_fmac_f32_e32 v177, v176, v175
	v_fma_f32 v173, -v173, v177, v174
	v_div_fmas_f32 v173, v173, v175, v177
	v_div_fixup_f32 v180, v173, v172, 1.0
	v_lshlrev_b64 v[182:183], 11, v[116:117]
	v_lshl_add_u64 v[182:183], s[0:1], 0, v[182:183]
	v_lshl_add_u64 v[182:183], v[182:183], 0, s[36:37]
	v_lshl_add_u64 v[182:183], v[182:183], 0, v[2:3]
	v_mul_f32_e32 v134, v180, v134
	v_mul_f32_e32 v135, v180, v135
	v_mul_f32_e32 v136, v180, v136
	v_mul_f32_e32 v137, v180, v137
	v_cvt_pk_bf16_f32 v184, v134, v135
	v_cvt_pk_bf16_f32 v185, v136, v137
	s_nop 0
	global_store_dwordx2 v[182:183], v[184:185], off offset:1536
	v_mul_f32_e32 v138, v180, v138
	v_mul_f32_e32 v139, v180, v139
	v_mul_f32_e32 v140, v180, v140
	v_mul_f32_e32 v141, v180, v141
	v_cvt_pk_bf16_f32 v186, v138, v139
	v_cvt_pk_bf16_f32 v187, v140, v141
	s_nop 0
	global_store_dwordx2 v[182:183], v[186:187], off offset:1568
	v_mul_f32_e32 v142, v180, v142
	v_mul_f32_e32 v143, v180, v143
	v_mul_f32_e32 v144, v180, v144
	v_mul_f32_e32 v145, v180, v145
	v_cvt_pk_bf16_f32 v188, v142, v143
	v_cvt_pk_bf16_f32 v189, v144, v145
	s_nop 0
	global_store_dwordx2 v[182:183], v[188:189], off offset:1600
	v_mul_f32_e32 v146, v180, v146
	v_mul_f32_e32 v147, v180, v147
	v_mul_f32_e32 v148, v180, v148
	v_mul_f32_e32 v149, v180, v149
	v_cvt_pk_bf16_f32 v190, v146, v147
	v_cvt_pk_bf16_f32 v191, v148, v149
	s_nop 0
	global_store_dwordx2 v[182:183], v[190:191], off offset:1632
	ds_read_b128 v[200:203], v128
	ds_read_b128 v[204:207], v128 offset:64
	ds_read_b128 v[208:211], v128 offset:2304
	ds_read_b128 v[212:215], v128 offset:2368
	ds_read_b128 v[216:219], v128 offset:4608
	ds_read_b128 v[220:223], v128 offset:4672
	ds_read_b128 v[224:227], v128 offset:6912
	ds_read_b128 v[228:231], v128 offset:6976
	s_waitcnt vmcnt(12)
	s_waitcnt lgkmcnt(4)
	v_mfma_f32_16x16x32_bf16 v[44:47], v[200:203], v[40:43], 0
	v_mfma_f32_16x16x32_bf16 v[48:51], v[208:211], v[40:43], 0
	v_mfma_f32_16x16x32_bf16 v[44:47], v[204:207], v[36:39], v[44:47]
	v_mfma_f32_16x16x32_bf16 v[48:51], v[212:215], v[36:39], v[48:51]
	ds_read_b128 v[200:203], v128 offset:9216
	ds_read_b128 v[204:207], v128 offset:9280
	ds_read_b128 v[208:211], v128 offset:11520
	ds_read_b128 v[212:215], v128 offset:11584
	s_waitcnt lgkmcnt(4)
	v_mfma_f32_16x16x32_bf16 v[52:55], v[216:219], v[40:43], 0
	v_mfma_f32_16x16x32_bf16 v[56:59], v[224:227], v[40:43], 0
	v_mfma_f32_16x16x32_bf16 v[52:55], v[220:223], v[36:39], v[52:55]
	v_mfma_f32_16x16x32_bf16 v[56:59], v[228:231], v[36:39], v[56:59]
	ds_read_b128 v[216:219], v128 offset:13824
	ds_read_b128 v[220:223], v128 offset:13888
	ds_read_b128 v[224:227], v128 offset:16128
	ds_read_b128 v[228:231], v128 offset:16192
	s_waitcnt lgkmcnt(4)
	v_mfma_f32_16x16x32_bf16 v[64:67], v[200:203], v[40:43], 0
	v_mfma_f32_16x16x32_bf16 v[68:71], v[208:211], v[40:43], 0
	v_mfma_f32_16x16x32_bf16 v[64:67], v[204:207], v[36:39], v[64:67]
	v_mfma_f32_16x16x32_bf16 v[68:71], v[212:215], v[36:39], v[68:71]
	ds_read_b128 v[200:203], v128 offset:18432
	ds_read_b128 v[204:207], v128 offset:18496
	ds_read_b128 v[208:211], v128 offset:20736
	ds_read_b128 v[212:215], v128 offset:20800
	s_waitcnt lgkmcnt(4)
	v_mfma_f32_16x16x32_bf16 v[72:75], v[216:219], v[40:43], 0
	v_mfma_f32_16x16x32_bf16 v[76:79], v[224:227], v[40:43], 0
	v_mfma_f32_16x16x32_bf16 v[72:75], v[220:223], v[36:39], v[72:75]
	v_mfma_f32_16x16x32_bf16 v[76:79], v[228:231], v[36:39], v[76:79]
	ds_read_b128 v[216:219], v128 offset:23040
	ds_read_b128 v[220:223], v128 offset:23104
	ds_read_b128 v[224:227], v128 offset:25344
	ds_read_b128 v[228:231], v128 offset:25408
	s_waitcnt lgkmcnt(4)
	v_mfma_f32_16x16x32_bf16 v[80:83], v[200:203], v[40:43], 0
	v_mfma_f32_16x16x32_bf16 v[84:87], v[208:211], v[40:43], 0
	v_mfma_f32_16x16x32_bf16 v[80:83], v[204:207], v[36:39], v[80:83]
	v_mfma_f32_16x16x32_bf16 v[84:87], v[212:215], v[36:39], v[84:87]
	ds_read_b128 v[200:203], v128 offset:27648
	ds_read_b128 v[204:207], v128 offset:27712
	ds_read_b128 v[208:211], v128 offset:29952
	ds_read_b128 v[212:215], v128 offset:30016
	s_waitcnt lgkmcnt(4)
	v_mfma_f32_16x16x32_bf16 v[88:91], v[216:219], v[40:43], 0
	v_mfma_f32_16x16x32_bf16 v[92:95], v[224:227], v[40:43], 0
	v_mfma_f32_16x16x32_bf16 v[88:91], v[220:223], v[36:39], v[88:91]
	v_mfma_f32_16x16x32_bf16 v[92:95], v[228:231], v[36:39], v[92:95]
	ds_read_b128 v[216:219], v128 offset:32256
	ds_read_b128 v[220:223], v128 offset:32320
	ds_read_b128 v[224:227], v128 offset:34560
	ds_read_b128 v[228:231], v128 offset:34624
	s_waitcnt lgkmcnt(4)
	v_mfma_f32_16x16x32_bf16 v[96:99], v[200:203], v[40:43], 0
	v_mfma_f32_16x16x32_bf16 v[100:103], v[208:211], v[40:43], 0
	v_mfma_f32_16x16x32_bf16 v[96:99], v[204:207], v[36:39], v[96:99]
	v_mfma_f32_16x16x32_bf16 v[100:103], v[212:215], v[36:39], v[100:103]
	s_waitcnt lgkmcnt(0)
	v_mfma_f32_16x16x32_bf16 v[104:107], v[216:219], v[40:43], 0
	v_mfma_f32_16x16x32_bf16 v[130:133], v[224:227], v[40:43], 0
	v_mfma_f32_16x16x32_bf16 v[104:107], v[220:223], v[36:39], v[104:107]
	v_mfma_f32_16x16x32_bf16 v[130:133], v[228:231], v[36:39], v[130:133]
	s_nop 7
	v_max3_f32 v154, v44, v45, s13
	v_max3_f32 v154, v46, v47, v154
	v_max3_f32 v154, v48, v49, v154
	v_max3_f32 v154, v50, v51, v154
	v_max3_f32 v154, v52, v53, v154
	v_max3_f32 v154, v54, v55, v154
	v_max3_f32 v154, v56, v57, v154
	v_max3_f32 v154, v58, v59, v154
	v_max3_f32 v154, v64, v65, v154
	v_max3_f32 v154, v66, v67, v154
	v_max3_f32 v154, v68, v69, v154
	v_max3_f32 v154, v70, v71, v154
	v_max3_f32 v154, v72, v73, v154
	v_max3_f32 v154, v74, v75, v154
	v_max3_f32 v154, v76, v77, v154
	v_max3_f32 v154, v78, v79, v154
	v_max3_f32 v154, v80, v81, v154
	v_max3_f32 v154, v82, v83, v154
	v_max3_f32 v154, v84, v85, v154
	v_max3_f32 v154, v86, v87, v154
	v_max3_f32 v154, v88, v89, v154
	v_max3_f32 v154, v90, v91, v154
	v_max3_f32 v154, v92, v93, v154
	v_max3_f32 v154, v94, v95, v154
	v_max3_f32 v154, v96, v97, v154
	v_max3_f32 v154, v98, v99, v154
	v_max3_f32 v154, v100, v101, v154
	v_max3_f32 v154, v102, v103, v154
	v_max3_f32 v154, v104, v105, v154
	v_max3_f32 v154, v106, v107, v154
	v_max3_f32 v154, v130, v131, v154
	v_max3_f32 v154, v132, v133, v154
	ds_bpermute_b32 v155, v126, v154
	s_waitcnt lgkmcnt(0)
	v_max_f32_e32 v154, v154, v155
	ds_bpermute_b32 v155, v127, v154
	s_waitcnt lgkmcnt(0)
	v_max_f32_e32 v154, v154, v155
	v_sub_f32_e32 v44, v44, v154
	v_exp_f32_e32 v44, v44
	v_sub_f32_e32 v45, v45, v154
	v_exp_f32_e32 v45, v45
	v_add_f32_e32 v172, 0, v44
	v_sub_f32_e32 v46, v46, v154
	v_exp_f32_e32 v46, v46
	v_add_f32_e32 v172, v45, v172
	v_sub_f32_e32 v47, v47, v154
	v_exp_f32_e32 v47, v47
	v_add_f32_e32 v172, v46, v172
	v_sub_f32_e32 v48, v48, v154
	v_exp_f32_e32 v48, v48
	v_add_f32_e32 v172, v47, v172
	v_sub_f32_e32 v49, v49, v154
	v_exp_f32_e32 v49, v49
	v_add_f32_e32 v172, v48, v172
	v_sub_f32_e32 v50, v50, v154
	v_exp_f32_e32 v50, v50
	v_add_f32_e32 v172, v49, v172
	v_sub_f32_e32 v51, v51, v154
	v_exp_f32_e32 v51, v51
	v_add_f32_e32 v172, v50, v172
	v_sub_f32_e32 v52, v52, v154
	v_exp_f32_e32 v52, v52
	v_add_f32_e32 v172, v51, v172
	v_sub_f32_e32 v53, v53, v154
	v_exp_f32_e32 v53, v53
	v_add_f32_e32 v172, v52, v172
	v_sub_f32_e32 v54, v54, v154
	v_exp_f32_e32 v54, v54
	v_add_f32_e32 v172, v53, v172
	v_sub_f32_e32 v55, v55, v154
	v_exp_f32_e32 v55, v55
	v_add_f32_e32 v172, v54, v172
	v_sub_f32_e32 v56, v56, v154
	v_exp_f32_e32 v56, v56
	v_add_f32_e32 v172, v55, v172
	v_sub_f32_e32 v57, v57, v154
	v_exp_f32_e32 v57, v57
	v_add_f32_e32 v172, v56, v172
	v_sub_f32_e32 v58, v58, v154
	v_exp_f32_e32 v58, v58
	v_add_f32_e32 v172, v57, v172
	v_sub_f32_e32 v59, v59, v154
	v_exp_f32_e32 v59, v59
	v_add_f32_e32 v172, v58, v172
	v_sub_f32_e32 v64, v64, v154
	v_exp_f32_e32 v64, v64
	v_add_f32_e32 v172, v59, v172
	v_sub_f32_e32 v65, v65, v154
	v_exp_f32_e32 v65, v65
	v_add_f32_e32 v172, v64, v172
	v_sub_f32_e32 v66, v66, v154
	v_exp_f32_e32 v66, v66
	v_add_f32_e32 v172, v65, v172
	v_sub_f32_e32 v67, v67, v154
	v_exp_f32_e32 v67, v67
	v_add_f32_e32 v172, v66, v172
	v_sub_f32_e32 v68, v68, v154
	v_exp_f32_e32 v68, v68
	v_add_f32_e32 v172, v67, v172
	v_sub_f32_e32 v69, v69, v154
	v_exp_f32_e32 v69, v69
	v_add_f32_e32 v172, v68, v172
	v_sub_f32_e32 v70, v70, v154
	v_exp_f32_e32 v70, v70
	v_add_f32_e32 v172, v69, v172
	v_sub_f32_e32 v71, v71, v154
	v_exp_f32_e32 v71, v71
	v_add_f32_e32 v172, v70, v172
	v_sub_f32_e32 v72, v72, v154
	v_exp_f32_e32 v72, v72
	v_add_f32_e32 v172, v71, v172
	v_sub_f32_e32 v73, v73, v154
	v_exp_f32_e32 v73, v73
	v_add_f32_e32 v172, v72, v172
	v_sub_f32_e32 v74, v74, v154
	v_exp_f32_e32 v74, v74
	v_add_f32_e32 v172, v73, v172
	v_sub_f32_e32 v75, v75, v154
	v_exp_f32_e32 v75, v75
	v_add_f32_e32 v172, v74, v172
	v_sub_f32_e32 v76, v76, v154
	v_exp_f32_e32 v76, v76
	v_add_f32_e32 v172, v75, v172
	v_sub_f32_e32 v77, v77, v154
	v_exp_f32_e32 v77, v77
	v_add_f32_e32 v172, v76, v172
	v_sub_f32_e32 v78, v78, v154
	v_exp_f32_e32 v78, v78
	v_add_f32_e32 v172, v77, v172
	v_sub_f32_e32 v79, v79, v154
	v_exp_f32_e32 v79, v79
	v_add_f32_e32 v172, v78, v172
	v_sub_f32_e32 v80, v80, v154
	v_exp_f32_e32 v80, v80
	v_add_f32_e32 v172, v79, v172
	v_sub_f32_e32 v81, v81, v154
	v_exp_f32_e32 v81, v81
	v_add_f32_e32 v172, v80, v172
	v_sub_f32_e32 v82, v82, v154
	v_exp_f32_e32 v82, v82
	v_add_f32_e32 v172, v81, v172
	v_sub_f32_e32 v83, v83, v154
	v_exp_f32_e32 v83, v83
	v_add_f32_e32 v172, v82, v172
	v_sub_f32_e32 v84, v84, v154
	v_exp_f32_e32 v84, v84
	v_add_f32_e32 v172, v83, v172
	v_sub_f32_e32 v85, v85, v154
	v_exp_f32_e32 v85, v85
	v_add_f32_e32 v172, v84, v172
	v_sub_f32_e32 v86, v86, v154
	v_exp_f32_e32 v86, v86
	v_add_f32_e32 v172, v85, v172
	v_sub_f32_e32 v87, v87, v154
	v_exp_f32_e32 v87, v87
	v_add_f32_e32 v172, v86, v172
	v_sub_f32_e32 v88, v88, v154
	v_exp_f32_e32 v88, v88
	v_add_f32_e32 v172, v87, v172
	v_sub_f32_e32 v89, v89, v154
	v_exp_f32_e32 v89, v89
	v_add_f32_e32 v172, v88, v172
	v_sub_f32_e32 v90, v90, v154
	v_exp_f32_e32 v90, v90
	v_add_f32_e32 v172, v89, v172
	v_sub_f32_e32 v91, v91, v154
	v_exp_f32_e32 v91, v91
	v_add_f32_e32 v172, v90, v172
	v_sub_f32_e32 v92, v92, v154
	v_exp_f32_e32 v92, v92
	v_add_f32_e32 v172, v91, v172
	v_sub_f32_e32 v93, v93, v154
	v_exp_f32_e32 v93, v93
	v_add_f32_e32 v172, v92, v172
	v_sub_f32_e32 v94, v94, v154
	v_exp_f32_e32 v94, v94
	v_add_f32_e32 v172, v93, v172
	v_sub_f32_e32 v95, v95, v154
	v_exp_f32_e32 v95, v95
	v_add_f32_e32 v172, v94, v172
	v_sub_f32_e32 v96, v96, v154
	v_exp_f32_e32 v96, v96
	v_add_f32_e32 v172, v95, v172
	v_sub_f32_e32 v97, v97, v154
	v_exp_f32_e32 v97, v97
	v_add_f32_e32 v172, v96, v172
	v_sub_f32_e32 v98, v98, v154
	v_exp_f32_e32 v98, v98
	v_add_f32_e32 v172, v97, v172
	v_sub_f32_e32 v99, v99, v154
	v_exp_f32_e32 v99, v99
	v_add_f32_e32 v172, v98, v172
	v_sub_f32_e32 v100, v100, v154
	v_exp_f32_e32 v100, v100
	v_add_f32_e32 v172, v99, v172
	v_sub_f32_e32 v101, v101, v154
	v_exp_f32_e32 v101, v101
	v_add_f32_e32 v172, v100, v172
	v_sub_f32_e32 v102, v102, v154
	v_exp_f32_e32 v102, v102
	v_add_f32_e32 v172, v101, v172
	v_sub_f32_e32 v103, v103, v154
	v_exp_f32_e32 v103, v103
	v_add_f32_e32 v172, v102, v172
	v_sub_f32_e32 v104, v104, v154
	v_exp_f32_e32 v104, v104
	v_add_f32_e32 v172, v103, v172
	v_sub_f32_e32 v105, v105, v154
	v_exp_f32_e32 v105, v105
	v_add_f32_e32 v172, v104, v172
	v_sub_f32_e32 v106, v106, v154
	v_exp_f32_e32 v106, v106
	v_add_f32_e32 v172, v105, v172
	v_sub_f32_e32 v107, v107, v154
	v_exp_f32_e32 v107, v107
	v_add_f32_e32 v172, v106, v172
	v_sub_f32_e32 v130, v130, v154
	v_exp_f32_e32 v130, v130
	v_add_f32_e32 v172, v107, v172
	v_sub_f32_e32 v131, v131, v154
	v_exp_f32_e32 v131, v131
	v_add_f32_e32 v172, v130, v172
	v_sub_f32_e32 v132, v132, v154
	v_exp_f32_e32 v132, v132
	v_add_f32_e32 v172, v131, v172
	v_sub_f32_e32 v133, v133, v154
	v_exp_f32_e32 v133, v133
	v_add_f32_e32 v172, v132, v172
	s_nop 0
	v_add_f32_e32 v172, v133, v172
	ds_bpermute_b32 v155, v126, v172
	s_waitcnt lgkmcnt(0)
	v_add_f32_e32 v172, v172, v155
	ds_bpermute_b32 v155, v127, v172
	s_waitcnt lgkmcnt(0)
	v_add_f32_e32 v172, v172, v155
	ds_read2_b64 v[200:203], v150 offset0:0 offset1:4
	ds_read2_b64 v[204:207], v151 offset0:0 offset1:4
	ds_read2_b64 v[208:211], v152 offset0:0 offset1:4
	ds_read2_b64 v[212:215], v153 offset0:0 offset1:4
	ds_read2_b64 v[216:219], v150 offset0:8 offset1:12
	ds_read2_b64 v[220:223], v151 offset0:8 offset1:12
	ds_read2_b64 v[224:227], v152 offset0:8 offset1:12
	ds_read2_b64 v[228:231], v153 offset0:8 offset1:12
	v_cvt_pk_bf16_f32 v44, v44, v45
	v_cvt_pk_bf16_f32 v45, v46, v47
	v_cvt_pk_bf16_f32 v46, v48, v49
	v_cvt_pk_bf16_f32 v47, v50, v51
	v_cvt_pk_bf16_f32 v52, v52, v53
	v_cvt_pk_bf16_f32 v53, v54, v55
	v_cvt_pk_bf16_f32 v54, v56, v57
	v_cvt_pk_bf16_f32 v55, v58, v59
	s_waitcnt lgkmcnt(4)
	s_nop 1
	v_mfma_f32_16x16x32_bf16 v[134:137], v[200:203], v[44:47], 0
	v_mfma_f32_16x16x32_bf16 v[138:141], v[204:207], v[44:47], 0
	v_mfma_f32_16x16x32_bf16 v[142:145], v[208:211], v[44:47], 0
	v_mfma_f32_16x16x32_bf16 v[146:149], v[212:215], v[44:47], 0
	ds_read2_b64 v[200:203], v150 offset0:16 offset1:20
	ds_read2_b64 v[204:207], v151 offset0:16 offset1:20
	ds_read2_b64 v[208:211], v152 offset0:16 offset1:20
	ds_read2_b64 v[212:215], v153 offset0:16 offset1:20
	v_cvt_pk_bf16_f32 v64, v64, v65
	v_cvt_pk_bf16_f32 v65, v66, v67
	v_cvt_pk_bf16_f32 v66, v68, v69
	v_cvt_pk_bf16_f32 v67, v70, v71
	s_waitcnt lgkmcnt(4)
	s_nop 1
	v_mfma_f32_16x16x32_bf16 v[134:137], v[216:219], v[52:55], v[134:137]
	v_mfma_f32_16x16x32_bf16 v[138:141], v[220:223], v[52:55], v[138:141]
	v_mfma_f32_16x16x32_bf16 v[142:145], v[224:227], v[52:55], v[142:145]
	v_mfma_f32_16x16x32_bf16 v[146:149], v[228:231], v[52:55], v[146:149]
	ds_read2_b64 v[216:219], v150 offset0:24 offset1:28
	ds_read2_b64 v[220:223], v151 offset0:24 offset1:28
	ds_read2_b64 v[224:227], v152 offset0:24 offset1:28
	ds_read2_b64 v[228:231], v153 offset0:24 offset1:28
	v_cvt_pk_bf16_f32 v72, v72, v73
	v_cvt_pk_bf16_f32 v73, v74, v75
	v_cvt_pk_bf16_f32 v74, v76, v77
	v_cvt_pk_bf16_f32 v75, v78, v79
	s_waitcnt lgkmcnt(4)
	s_nop 1
	v_mfma_f32_16x16x32_bf16 v[134:137], v[200:203], v[64:67], v[134:137]
	v_mfma_f32_16x16x32_bf16 v[138:141], v[204:207], v[64:67], v[138:141]
	v_mfma_f32_16x16x32_bf16 v[142:145], v[208:211], v[64:67], v[142:145]
	v_mfma_f32_16x16x32_bf16 v[146:149], v[212:215], v[64:67], v[146:149]
	ds_read2_b64 v[200:203], v150 offset0:32 offset1:36
	ds_read2_b64 v[204:207], v151 offset0:32 offset1:36
	ds_read2_b64 v[208:211], v152 offset0:32 offset1:36
	ds_read2_b64 v[212:215], v153 offset0:32 offset1:36
	v_cvt_pk_bf16_f32 v80, v80, v81
	v_cvt_pk_bf16_f32 v81, v82, v83
	v_cvt_pk_bf16_f32 v82, v84, v85
	v_cvt_pk_bf16_f32 v83, v86, v87
	s_waitcnt lgkmcnt(4)
	s_nop 1
	v_mfma_f32_16x16x32_bf16 v[134:137], v[216:219], v[72:75], v[134:137]
	v_mfma_f32_16x16x32_bf16 v[138:141], v[220:223], v[72:75], v[138:141]
	v_mfma_f32_16x16x32_bf16 v[142:145], v[224:227], v[72:75], v[142:145]
	v_mfma_f32_16x16x32_bf16 v[146:149], v[228:231], v[72:75], v[146:149]
	ds_read2_b64 v[216:219], v150 offset0:40 offset1:44
	ds_read2_b64 v[220:223], v151 offset0:40 offset1:44
	ds_read2_b64 v[224:227], v152 offset0:40 offset1:44
	ds_read2_b64 v[228:231], v153 offset0:40 offset1:44
	v_cvt_pk_bf16_f32 v88, v88, v89
	v_cvt_pk_bf16_f32 v89, v90, v91
	v_cvt_pk_bf16_f32 v90, v92, v93
	v_cvt_pk_bf16_f32 v91, v94, v95
	s_waitcnt lgkmcnt(4)
	s_nop 1
	v_mfma_f32_16x16x32_bf16 v[134:137], v[200:203], v[80:83], v[134:137]
	v_mfma_f32_16x16x32_bf16 v[138:141], v[204:207], v[80:83], v[138:141]
	v_mfma_f32_16x16x32_bf16 v[142:145], v[208:211], v[80:83], v[142:145]
	v_mfma_f32_16x16x32_bf16 v[146:149], v[212:215], v[80:83], v[146:149]
	ds_read2_b64 v[200:203], v150 offset0:48 offset1:52
	ds_read2_b64 v[204:207], v151 offset0:48 offset1:52
	ds_read2_b64 v[208:211], v152 offset0:48 offset1:52
	ds_read2_b64 v[212:215], v153 offset0:48 offset1:52
	v_cvt_pk_bf16_f32 v96, v96, v97
	v_cvt_pk_bf16_f32 v97, v98, v99
	v_cvt_pk_bf16_f32 v98, v100, v101
	v_cvt_pk_bf16_f32 v99, v102, v103
	s_waitcnt lgkmcnt(4)
	s_nop 1
	v_mfma_f32_16x16x32_bf16 v[134:137], v[216:219], v[88:91], v[134:137]
	v_mfma_f32_16x16x32_bf16 v[138:141], v[220:223], v[88:91], v[138:141]
	v_mfma_f32_16x16x32_bf16 v[142:145], v[224:227], v[88:91], v[142:145]
	v_mfma_f32_16x16x32_bf16 v[146:149], v[228:231], v[88:91], v[146:149]
	ds_read2_b64 v[216:219], v150 offset0:56 offset1:60
	ds_read2_b64 v[220:223], v151 offset0:56 offset1:60
	ds_read2_b64 v[224:227], v152 offset0:56 offset1:60
	ds_read2_b64 v[228:231], v153 offset0:56 offset1:60
	v_cvt_pk_bf16_f32 v104, v104, v105
	v_cvt_pk_bf16_f32 v105, v106, v107
	v_cvt_pk_bf16_f32 v106, v130, v131
	v_cvt_pk_bf16_f32 v107, v132, v133
	s_waitcnt lgkmcnt(4)
	s_nop 1
	v_mfma_f32_16x16x32_bf16 v[134:137], v[200:203], v[96:99], v[134:137]
	v_mfma_f32_16x16x32_bf16 v[138:141], v[204:207], v[96:99], v[138:141]
	v_mfma_f32_16x16x32_bf16 v[142:145], v[208:211], v[96:99], v[142:145]
	v_mfma_f32_16x16x32_bf16 v[146:149], v[212:215], v[96:99], v[146:149]
	s_waitcnt lgkmcnt(0)
	s_nop 1
	v_mfma_f32_16x16x32_bf16 v[134:137], v[216:219], v[104:107], v[134:137]
	v_mfma_f32_16x16x32_bf16 v[138:141], v[220:223], v[104:107], v[138:141]
	v_mfma_f32_16x16x32_bf16 v[142:145], v[224:227], v[104:107], v[142:145]
	v_mfma_f32_16x16x32_bf16 v[146:149], v[228:231], v[104:107], v[146:149]
	v_div_scale_f32 v173, s[8:9], v172, v172, 1.0
	v_rcp_f32_e32 v175, v173
	s_nop 0
	v_fma_f32 v176, -v173, v175, 1.0
	v_fmac_f32_e32 v175, v176, v175
	v_div_scale_f32 v174, vcc, 1.0, v172, 1.0
	v_mul_f32_e32 v177, v174, v175
	v_fma_f32 v176, -v173, v177, v174
	v_fmac_f32_e32 v177, v176, v175
	v_fma_f32 v173, -v173, v177, v174
	v_div_fmas_f32 v173, v173, v175, v177
	v_div_fixup_f32 v180, v173, v172, 1.0
	v_lshlrev_b64 v[182:183], 11, v[114:115]
	v_lshl_add_u64 v[182:183], s[0:1], 0, v[182:183]
	v_lshl_add_u64 v[182:183], v[182:183], 0, s[36:37]
	v_lshl_add_u64 v[182:183], v[182:183], 0, v[2:3]
	v_mul_f32_e32 v134, v180, v134
	v_mul_f32_e32 v135, v180, v135
	v_mul_f32_e32 v136, v180, v136
	v_mul_f32_e32 v137, v180, v137
	v_cvt_pk_bf16_f32 v184, v134, v135
	v_cvt_pk_bf16_f32 v185, v136, v137
	s_nop 0
	global_store_dwordx2 v[182:183], v[184:185], off offset:1536
	v_mul_f32_e32 v138, v180, v138
	v_mul_f32_e32 v139, v180, v139
	v_mul_f32_e32 v140, v180, v140
	v_mul_f32_e32 v141, v180, v141
	v_cvt_pk_bf16_f32 v186, v138, v139
	v_cvt_pk_bf16_f32 v187, v140, v141
	s_nop 0
	global_store_dwordx2 v[182:183], v[186:187], off offset:1568
	v_mul_f32_e32 v142, v180, v142
	v_mul_f32_e32 v143, v180, v143
	v_mul_f32_e32 v144, v180, v144
	v_mul_f32_e32 v145, v180, v145
	v_cvt_pk_bf16_f32 v188, v142, v143
	v_cvt_pk_bf16_f32 v189, v144, v145
	s_nop 0
	global_store_dwordx2 v[182:183], v[188:189], off offset:1600
	v_mul_f32_e32 v146, v180, v146
	v_mul_f32_e32 v147, v180, v147
	v_mul_f32_e32 v148, v180, v148
	v_mul_f32_e32 v149, v180, v149
	v_cvt_pk_bf16_f32 v190, v146, v147
	v_cvt_pk_bf16_f32 v191, v148, v149
	s_nop 0
	global_store_dwordx2 v[182:183], v[190:191], off offset:1632
	s_mov_b32 s13, s12
	s_andn2_b64 vcc, exec, s[6:7]
	s_barrier
	s_cbranch_vccz .LBB0_582
